# P4a: xor-1/2/4/8 hops of the eleven wave sums via DPP adds instead of ds_bpermute+wait+add (44 LDS ops fewer per token)
# baseline (speedup 1.0000x reference)
; __device__ __forceinline__ float bflo(unsigned u) { return __uint_as_float(u << 16); }
; __device__ __forceinline__ float bfhi(unsigned u) { return __uint_as_float(u & 0xffff0000u); }
; __device__ __forceinline__ float bf1(unsigned short u) { return __uint_as_float(((unsigned)u) << 16); }
; __device__ __forceinline__ void phase4a(const Args& a, int gw, int NGW, int lane_) {
;     ...
;         { const float c0 = bflo(cur.cq.x), c1 = bfhi(cur.cq.x), c2 = bflo(cur.cq.y), c3 = bfhi(cur.cq.y), d0 = bflo(cur.ckv), d1 = bfhi(cur.ckv);
;           red[0] = (c0 * c0 + c1 * c1) + (c2 * c2 + c3 * c3); red[1] = d0 * d0 + d1 * d1; red[2] = kpe * kpe; }
; #pragma unroll
;         for (int h = 0; h < NH; ++h) { qv[h][0] = bf1(cur.q[h][0]); qv[h][1] = bf1(cur.q[h][1]); qv[h][2] = bf1(cur.q[h][2]); kv[h][0] = bf1(cur.k[h][0]); kv[h][1] = bf1(cur.k[h][1]);
;             red[3 + h] = qv[h][0] * qv[h][0] + qv[h][1] * qv[h][1] + qv[h][2] * qv[h][2]; red[7 + h] = kv[h][0] * kv[h][0] + kv[h][1] * kv[h][1]; }
; #pragma unroll
;         for (int o = 1; o < 64; o <<= 1) {
; #pragma unroll
;             for (int e = 0; e < 11; ++e) red[e] += __shfl_xor(red[e], o);
;         }
.LBB0_383:
	s_waitcnt vmcnt(1)
	v_lshlrev_b32_e32 v84, 16, v80
	v_and_b32_e32 v85, 0xffff0000, v80
	v_lshlrev_b32_e32 v81, 16, v17
	v_lshlrev_b32_e32 v80, 16, v16
	v_and_b32_e32 v17, 0xffff0000, v17
	v_and_b32_e32 v16, 0xffff0000, v16
	v_pk_mul_f32 v[16:17], v[16:17], v[16:17]
	v_lshlrev_b32_e32 v88, 16, v79
	v_pk_fma_f32 v[96:97], v[80:81], v[80:81], v[16:17]
	v_lshlrev_b32_e32 v79, 16, v77
	v_lshlrev_b32_e32 v81, 16, v76
	v_lshlrev_b32_e32 v77, 16, v75
	v_lshlrev_b32_e32 v76, 16, v74
	v_lshlrev_b32_e32 v74, 16, v71
	v_pk_mul_f32 v[98:99], v[84:85], v[84:85]
	v_lshlrev_b32_e32 v80, 16, v78
	v_lshlrev_b32_e32 v78, 16, v73
	v_lshlrev_b32_e32 v84, 16, v20
	v_mul_f32_e32 v20, v77, v77
	v_lshlrev_b32_e32 v73, 16, v70
	v_mul_f32_e32 v90, v74, v74
	v_lshlrev_b32_e32 v87, 16, v23
	v_fmac_f32_e32 v20, v76, v76
	v_lshlrev_b32_e32 v75, 16, v19
	v_fmac_f32_e32 v90, v73, v73
	v_lshlrev_b32_e32 v86, 16, v22
	v_mul_f32_e32 v23, v87, v87
	v_fmac_f32_e32 v20, v78, v78
	v_fmac_f32_e32 v90, v75, v75
	v_mul_f32_e32 v22, v80, v80
	v_fmac_f32_e32 v23, v86, v86
	v_lshlrev_b32_e32 v71, 16, v25
	v_and_b32_e32 v17, 0xffff0000, v89
	v_lshlrev_b32_e32 v16, 16, v89
	v_fmac_f32_e32 v22, v79, v79
	v_lshlrev_b32_e32 v83, 16, v82
	v_lshlrev_b32_e32 v82, 16, v72
	v_lshlrev_b32_e32 v72, 16, v18
	v_pk_mul_f32 v[18:19], v[16:17], v[16:17]
	v_fmac_f32_e32 v22, v81, v81
	v_lshlrev_b32_e32 v85, 16, v21
	v_fma_f32 v19, v72, v72, v19
	v_mul_f32_e32 v21, v85, v85
	v_mul_f32_e32 v91, v83, v83
	v_add_f32_e32 v101, v18, v19
	v_fmac_f32_e32 v21, v84, v84
	v_fmac_f32_e32 v91, v82, v82
	v_lshlrev_b32_e32 v70, 16, v24
	v_mul_f32_e32 v24, v71, v71
	v_fmac_f32_e32 v24, v70, v70
	v_add_f32_dpp v20, v20, v20 quad_perm:[1,0,3,2] row_mask:0xf bank_mask:0xf
	v_add_f32_dpp v25, v90, v90 quad_perm:[1,0,3,2] row_mask:0xf bank_mask:0xf
	v_add_f32_dpp v23, v23, v23 quad_perm:[1,0,3,2] row_mask:0xf bank_mask:0xf
	v_add_f32_dpp v22, v22, v22 quad_perm:[1,0,3,2] row_mask:0xf bank_mask:0xf
	v_add_f32_dpp v21, v21, v21 quad_perm:[1,0,3,2] row_mask:0xf bank_mask:0xf
	v_add_f32_dpp v89, v91, v91 quad_perm:[1,0,3,2] row_mask:0xf bank_mask:0xf
	v_add_f32_dpp v24, v24, v24 quad_perm:[1,0,3,2] row_mask:0xf bank_mask:0xf
	v_add_f32_dpp v20, v20, v20 quad_perm:[2,3,0,1] row_mask:0xf bank_mask:0xf
	v_add_f32_dpp v22, v22, v22 quad_perm:[2,3,0,1] row_mask:0xf bank_mask:0xf
	v_add_f32_dpp v25, v25, v25 quad_perm:[2,3,0,1] row_mask:0xf bank_mask:0xf
	v_add_f32_dpp v21, v21, v21 quad_perm:[2,3,0,1] row_mask:0xf bank_mask:0xf
	v_add_f32_dpp v24, v24, v24 quad_perm:[2,3,0,1] row_mask:0xf bank_mask:0xf
	v_add_f32_dpp v23, v23, v23 quad_perm:[2,3,0,1] row_mask:0xf bank_mask:0xf
	v_add_f32_dpp v89, v89, v89 quad_perm:[2,3,0,1] row_mask:0xf bank_mask:0xf
	v_add_f32_dpp v22, v22, v22 row_half_mirror row_mask:0xf bank_mask:0xf
	v_add_f32_dpp v25, v25, v25 row_half_mirror row_mask:0xf bank_mask:0xf
	v_add_f32_dpp v21, v21, v21 row_half_mirror row_mask:0xf bank_mask:0xf
	v_add_f32_dpp v20, v20, v20 row_half_mirror row_mask:0xf bank_mask:0xf
	v_add_f32_dpp v23, v23, v23 row_half_mirror row_mask:0xf bank_mask:0xf
	v_add_f32_dpp v89, v89, v89 row_half_mirror row_mask:0xf bank_mask:0xf
	v_add_f32_dpp v22, v22, v22 row_mirror row_mask:0xf bank_mask:0xf
	v_add_f32_dpp v25, v25, v25 row_mirror row_mask:0xf bank_mask:0xf
	ds_bpermute_b32 v94, v39, v22
	v_add_f32_dpp v24, v24, v24 row_half_mirror row_mask:0xf bank_mask:0xf
	v_add_f32_dpp v20, v20, v20 row_mirror row_mask:0xf bank_mask:0xf
	v_add_f32_dpp v23, v23, v23 row_mirror row_mask:0xf bank_mask:0xf
	v_add_f32_dpp v92, v89, v89 row_mirror row_mask:0xf bank_mask:0xf
	s_waitcnt lgkmcnt(0)
	v_add_f32_e32 v89, v22, v94
	ds_bpermute_b32 v22, v39, v20
	ds_bpermute_b32 v90, v39, v23
	v_add_f32_dpp v95, v24, v24 row_mirror row_mask:0xf bank_mask:0xf
	ds_bpermute_b32 v24, v39, v25
	s_waitcnt lgkmcnt(2)
	v_add_f32_e32 v93, v20, v22
	s_waitcnt lgkmcnt(1)
	v_add_f32_e32 v90, v23, v90
	v_mov_b32_e32 v22, v98
	v_mov_b32_e32 v23, v96
	v_mov_b32_e32 v96, v99
	v_mul_f32_e32 v100, v88, v88
	v_pk_add_f32 v[22:23], v[22:23], v[96:97]
	v_add_f32_dpp v21, v21, v21 row_mirror row_mask:0xf bank_mask:0xf
	s_waitcnt lgkmcnt(0)
	v_add_f32_e32 v94, v25, v24
	ds_bpermute_b32 v91, v39, v21
	v_add_f32_dpp v18, v100, v100 quad_perm:[1,0,3,2] row_mask:0xf bank_mask:0xf
	v_add_f32_dpp v19, v101, v101 quad_perm:[1,0,3,2] row_mask:0xf bank_mask:0xf
	ds_bpermute_b32 v102, v39, v92
	v_add_f32_dpp v22, v22, v22 quad_perm:[1,0,3,2] row_mask:0xf bank_mask:0xf
	v_add_f32_dpp v23, v23, v23 quad_perm:[1,0,3,2] row_mask:0xf bank_mask:0xf
	s_waitcnt lgkmcnt(1)
	v_add_f32_e32 v91, v21, v91
	s_waitcnt lgkmcnt(0)
	v_add_f32_e32 v92, v92, v102
	ds_bpermute_b32 v102, v39, v95
	v_add_f32_dpp v18, v18, v18 quad_perm:[2,3,0,1] row_mask:0xf bank_mask:0xf
	v_add_f32_dpp v19, v19, v19 quad_perm:[2,3,0,1] row_mask:0xf bank_mask:0xf
	v_add_f32_dpp v22, v22, v22 quad_perm:[2,3,0,1] row_mask:0xf bank_mask:0xf
	v_add_f32_dpp v23, v23, v23 quad_perm:[2,3,0,1] row_mask:0xf bank_mask:0xf
	s_waitcnt lgkmcnt(0)
	v_add_f32_e32 v96, v95, v102
	s_waitcnt vmcnt(0)
	v_cvt_f32_i32_e32 v4, v4
	v_add_f32_dpp v18, v18, v18 row_half_mirror row_mask:0xf bank_mask:0xf
	v_add_f32_dpp v19, v19, v19 row_half_mirror row_mask:0xf bank_mask:0xf
	v_add_f32_dpp v22, v22, v22 row_half_mirror row_mask:0xf bank_mask:0xf
	v_add_f32_dpp v23, v23, v23 row_half_mirror row_mask:0xf bank_mask:0xf
	ds_bpermute_b32 v98, v34, v89
	ds_bpermute_b32 v99, v34, v93
	v_add_f32_dpp v18, v18, v18 row_mirror row_mask:0xf bank_mask:0xf
	v_add_f32_dpp v19, v19, v19 row_mirror row_mask:0xf bank_mask:0xf
	ds_bpermute_b32 v20, v39, v18
	v_add_f32_dpp v22, v22, v22 row_mirror row_mask:0xf bank_mask:0xf
	v_add_f32_dpp v23, v23, v23 row_mirror row_mask:0xf bank_mask:0xf
	ds_bpermute_b32 v21, v39, v19
	ds_bpermute_b32 v25, v39, v23
	ds_bpermute_b32 v24, v39, v22
	ds_bpermute_b32 v100, v34, v94
	ds_bpermute_b32 v101, v34, v90
	s_waitcnt lgkmcnt(4)
	v_pk_add_f32 v[18:19], v[18:19], v[20:21]
	ds_bpermute_b32 v20, v34, v18
	s_waitcnt lgkmcnt(3)
	v_pk_add_f32 v[22:23], v[22:23], v[24:25]
	ds_bpermute_b32 v21, v34, v19
	ds_bpermute_b32 v102, v34, v91
	ds_bpermute_b32 v103, v34, v92
	ds_bpermute_b32 v104, v34, v96
	ds_bpermute_b32 v25, v34, v23
	ds_bpermute_b32 v24, v34, v22
	v_mul_f32_e32 v95, v32, v4
	v_and_b32_e32 v97, 0x7fffffff, v95
	v_cmp_nlt_f32_e64 s[0:1], |v95|, s3
	s_and_saveexec_b64 s[4:5], s[0:1]
	s_xor_b64 s[22:23], exec, s[4:5]
	s_cbranch_execz .LBB0_385
; __device__ __forceinline__ void phase4a(const Args& a, int gw, int NGW, int lane_) {
;     ...
;         const float ang = (float)cur.pos * inv_freq; float sn, cs; sincosf(ang, &sn, &cs);
	v_lshrrev_b32_e32 v4, 23, v97
	v_add_u32_e32 v4, 0xffffff88, v4
	v_cmp_lt_u32_e32 vcc, 63, v4
	s_nop 1
	v_cndmask_b32_e32 v105, 0, v44, vcc
	v_add_u32_e32 v4, v105, v4
	v_cmp_lt_u32_e64 s[0:1], 31, v4
	s_nop 1
	v_cndmask_b32_e64 v105, 0, v45, s[0:1]
	v_add_u32_e32 v4, v105, v4
	v_cmp_lt_u32_e64 s[4:5], 31, v4
	s_nop 1
	v_cndmask_b32_e64 v105, 0, v45, s[4:5]
	v_add_u32_e32 v105, v105, v4
	v_and_b32_e32 v4, 0x7fffff, v97
	v_or_b32_e32 v118, 0x800000, v4
	v_mad_u64_u32 v[106:107], s[6:7], v118, s9, 0
	v_mov_b32_e32 v4, v107
	v_mad_u64_u32 v[108:109], s[6:7], v118, s10, v[4:5]
	v_mov_b32_e32 v4, v109
	v_mad_u64_u32 v[110:111], s[6:7], v118, s11, v[4:5]
	v_mov_b32_e32 v4, v111
	v_mad_u64_u32 v[112:113], s[6:7], v118, s15, v[4:5]
	v_mov_b32_e32 v4, v113
	v_mad_u64_u32 v[114:115], s[6:7], v118, s17, v[4:5]
	v_mov_b32_e32 v4, v115
	v_mad_u64_u32 v[116:117], s[6:7], v118, s24, v[4:5]
	v_mov_b32_e32 v4, v117
	v_mad_u64_u32 v[118:119], s[6:7], v118, s25, v[4:5]
	v_cndmask_b32_e32 v107, v116, v112, vcc
	v_cndmask_b32_e32 v4, v118, v114, vcc
	v_cndmask_b32_e32 v111, v119, v116, vcc
	v_cndmask_b32_e64 v109, v4, v107, s[0:1]
	v_cndmask_b32_e64 v4, v111, v4, s[0:1]
	v_cndmask_b32_e32 v111, v114, v110, vcc
	v_cndmask_b32_e64 v107, v107, v111, s[0:1]
	v_cndmask_b32_e64 v4, v4, v109, s[4:5]
	v_cndmask_b32_e64 v109, v109, v107, s[4:5]
	v_sub_u32_e32 v113, 32, v105
	v_alignbit_b32 v114, v4, v109, v113
	v_cmp_eq_u32_e64 s[6:7], 0, v105
	v_cndmask_b32_e32 v106, v110, v106, vcc
	s_nop 0
	v_cndmask_b32_e64 v105, v114, v4, s[6:7]
	v_cndmask_b32_e32 v4, v112, v108, vcc
	v_cndmask_b32_e64 v108, v111, v4, s[0:1]
	v_cndmask_b32_e64 v107, v107, v108, s[4:5]
	v_alignbit_b32 v111, v109, v107, v113
	v_cndmask_b32_e64 v109, v111, v109, s[6:7]
	v_bfe_u32 v114, v105, 29, 1
	v_cndmask_b32_e64 v4, v4, v106, s[0:1]
	v_alignbit_b32 v111, v105, v109, 30
	v_sub_u32_e32 v115, 0, v114
	v_cndmask_b32_e64 v4, v108, v4, s[4:5]
	v_xor_b32_e32 v111, v111, v115
	v_alignbit_b32 v106, v107, v4, v113
	v_cndmask_b32_e64 v106, v106, v107, s[6:7]
	v_ffbh_u32_e32 v108, v111
	v_alignbit_b32 v107, v109, v106, 30
	v_min_u32_e32 v108, 32, v108
	v_alignbit_b32 v4, v106, v4, 30
	v_xor_b32_e32 v107, v107, v115
	v_sub_u32_e32 v109, 31, v108
	v_xor_b32_e32 v4, v4, v115
	v_alignbit_b32 v110, v111, v107, v109
	v_alignbit_b32 v4, v107, v4, v109
	v_alignbit_b32 v106, v110, v4, 9
	v_ffbh_u32_e32 v107, v106
	v_min_u32_e32 v107, 32, v107
	v_lshrrev_b32_e32 v112, 29, v105
	v_not_b32_e32 v109, v107
	v_alignbit_b32 v4, v106, v4, v109
	v_lshlrev_b32_e32 v106, 31, v112
	v_or_b32_e32 v109, 0x33000000, v106
	v_add_lshl_u32 v107, v107, v108, 23
	v_lshrrev_b32_e32 v4, 9, v4
	v_sub_u32_e32 v107, v109, v107
	v_or_b32_e32 v106, 0.5, v106
	v_lshlrev_b32_e32 v108, 23, v108
	v_or_b32_e32 v4, v107, v4
	v_lshrrev_b32_e32 v107, 9, v110
	v_sub_u32_e32 v106, v106, v108
	v_or_b32_e32 v106, v107, v106
	v_mul_f32_e32 v107, 0x3fc90fda, v106
	v_fma_f32 v108, v106, s26, -v107
	v_fmac_f32_e32 v108, 0x33a22168, v106
	v_fmac_f32_e32 v108, 0x3fc90fda, v4
	v_lshrrev_b32_e32 v105, 30, v105
	v_add_f32_e32 v4, v107, v108
	v_add_u32_e32 v105, v114, v105
